# cmp-L2: the wave's two rows share the W2 loads (one v_pk_fma_f32 per k for both accumulators); trampolines for the two kernel-spanning branches
# baseline (speedup 1.0000x reference)
; __device__ __forceinline__ unsigned cvt_pk_bf16(float lo, float hi) { unsigned r; asm volatile("v_cvt_pk_bf16_f32 %0, %1, %2" : "=v"(r) : "v"(lo), "v"(hi)); return r; }
; __device__ __forceinline__ float bflo(unsigned w) { return __uint_as_float(w << 16); }
; __device__ __forceinline__ float bfhi(unsigned w) { return __uint_as_float(w & 0xffff0000u); }
; __device__ __forceinline__ float wave_sum(float x) { return x32sum(x16sum(sum16(x))); }
; #define INP(i) ((const float*)ldp(tab, (i)))
; __global__ void __launch_bounds__(512, 2) mega(Args a) {
;     ...
;             for (int prep_ = 0; prep_ < PROBE_CL2; ++prep_) for (int it = gw; it < 2048 * 2; it += NGW) { const int R = it >> 1, kv = it & 1, i = R >> 2, gg = R & 3;
;                 float acc = 0.f;
;                 if (R < 2044) {
;                     const bf16_t* hr = HID + ((size_t)kv * 2048 + R) * 256; const u32x2 hw = *(const u32x2*)(hr + lane * 4);
;                     const float h0 = bflo(hw.x), h1 = bfhi(hw.x), h2 = bflo(hw.y), h3 = bfhi(hw.y); const float* w2 = INP(kv ? I_W2V : I_W2K) + lane;
; #pragma unroll 16
;                     for (int jj = 0; jj < 64; ++jj) {
;                         acc += __int_as_float(__builtin_amdgcn_readlane(__float_as_int(h0), jj)) * w2[(jj * 4 + 0) * 64];
;                         acc += __int_as_float(__builtin_amdgcn_readlane(__float_as_int(h1), jj)) * w2[(jj * 4 + 1) * 64];
;                         acc += __int_as_float(__builtin_amdgcn_readlane(__float_as_int(h2), jj)) * w2[(jj * 4 + 2) * 64];
;                         acc += __int_as_float(__builtin_amdgcn_readlane(__float_as_int(h3), jj)) * w2[(jj * 4 + 3) * 64]; }
;                 }
;                 if (kv == 0) { const float rr = __builtin_amdgcn_rsqf(wave_sum(acc * acc) * (1.0f / 64.0f) + EPS); const float y = acc * rr * INP(I_GKC)[lane];
;                     KC[((size_t)gg * 512 + i) * 64 + lane] = (bf16_t)(cvt_pk_bf16(y, 0.f) & 0xffffu); }
;                 else VCT[((size_t)gg * 64 + lane) * 512 + i] = (bf16_t)(cvt_pk_bf16(acc, 0.f) & 0xffffu);
.LBB0_357:
	s_ashr_i32 s5, s9, 1
	s_cmpk_gt_i32 s5, 0x7fb
	v_mov_b32_e32 v13, 0
	s_cbranch_scc1 .LBB0_360
	s_cmp_lg_u32 s9, s62
	s_cbranch_scc0 .Lc2_first
	v_mov_b32_e32 v13, v165
	s_branch .LBB0_360
.Lc2_first:
	s_ashr_i32 s2, s5, 31
	s_add_u32 s6, s3, s5
	s_addc_u32 s7, 0, s2
	s_lshl_b64 s[6:7], s[6:7], 9
	v_lshl_add_u64 v[8:9], v[4:5], 0, s[6:7]
	s_mov_b32 s94, 0x80000
	v_mov_b32_e32 v111, v64
	v_mov_b32_e32 v110, s94
	v_lshl_add_u64 v[110:111], v[8:9], 0, v[110:111]
	v_mov_b32_e32 v108, 0
	v_mov_b32_e32 v109, 0
	s_cmpk_gt_i32 s5, 0x3fb
	s_cbranch_scc1 .Lc2_norow2
	global_load_dwordx2 v[108:109], v[110:111], off
.Lc2_norow2:
	global_load_dwordx2 v[8:9], v[8:9], off
	v_mov_b32_e32 v13, 0
	s_mov_b32 s4, 0
	s_waitcnt vmcnt(0)
	v_lshlrev_b32_e32 v1, 16, v8
	v_and_b32_e32 v10, 0xffff0000, v8
	v_mov_b32_e32 v8, s8
	v_lshlrev_b32_e32 v11, 16, v9
	v_and_b32_e32 v12, 0xffff0000, v9
	v_lshlrev_b32_e32 v104, 16, v108
	v_and_b32_e32 v105, 0xffff0000, v108
	v_lshlrev_b32_e32 v106, 16, v109
	v_and_b32_e32 v107, 0xffff0000, v109
	v_mov_b32_e32 v108, 0
	v_mov_b32_e32 v109, 0
	ds_read_b64 v[8:9], v8
	s_waitcnt lgkmcnt(0)
	v_readfirstlane_b32 s7, v9
	v_readfirstlane_b32 s6, v8
	s_nop 3
	s_add_u32 s18, s6, 0x1000
	s_addc_u32 s19, s7, 0
	global_load_dword v72, v2, s[18:19] offset:-4096
	global_load_dword v73, v2, s[18:19] offset:-3840
	global_load_dword v74, v2, s[18:19] offset:-3584
	global_load_dword v75, v2, s[18:19] offset:-3328
	global_load_dword v76, v2, s[18:19] offset:-3072
	global_load_dword v77, v2, s[18:19] offset:-2816
	global_load_dword v78, v2, s[18:19] offset:-2560
	global_load_dword v79, v2, s[18:19] offset:-2304
	global_load_dword v80, v2, s[18:19] offset:-2048
	global_load_dword v81, v2, s[18:19] offset:-1792
	global_load_dword v82, v2, s[18:19] offset:-1536
	global_load_dword v83, v2, s[18:19] offset:-1280
	global_load_dword v84, v2, s[18:19] offset:-1024
	global_load_dword v85, v2, s[18:19] offset:-768
	global_load_dword v86, v2, s[18:19] offset:-512
	global_load_dword v87, v2, s[18:19] offset:-256
	global_load_dword v88, v2, s[18:19]
	global_load_dword v89, v2, s[18:19] offset:256
	global_load_dword v90, v2, s[18:19] offset:512
	global_load_dword v91, v2, s[18:19] offset:768
	global_load_dword v92, v2, s[18:19] offset:1024
	global_load_dword v93, v2, s[18:19] offset:1280
	global_load_dword v94, v2, s[18:19] offset:1536
	global_load_dword v95, v2, s[18:19] offset:1792
	global_load_dword v96, v2, s[18:19] offset:2048
	global_load_dword v97, v2, s[18:19] offset:2304
	global_load_dword v98, v2, s[18:19] offset:2560
	global_load_dword v99, v2, s[18:19] offset:2816
	global_load_dword v100, v2, s[18:19] offset:3072
	global_load_dword v101, v2, s[18:19] offset:3328
	global_load_dword v102, v2, s[18:19] offset:3584
	global_load_dword v103, v2, s[18:19] offset:3840
	s_add_u32 s18, s18, 0x2000
	s_addc_u32 s19, s19, 0
	global_load_dword v132, v2, s[18:19] offset:-4096
	global_load_dword v133, v2, s[18:19] offset:-3840
	global_load_dword v134, v2, s[18:19] offset:-3584
	global_load_dword v135, v2, s[18:19] offset:-3328
	global_load_dword v136, v2, s[18:19] offset:-3072
	global_load_dword v137, v2, s[18:19] offset:-2816
	global_load_dword v138, v2, s[18:19] offset:-2560
	global_load_dword v139, v2, s[18:19] offset:-2304
	global_load_dword v140, v2, s[18:19] offset:-2048
	global_load_dword v141, v2, s[18:19] offset:-1792
	global_load_dword v142, v2, s[18:19] offset:-1536
	global_load_dword v143, v2, s[18:19] offset:-1280
	global_load_dword v144, v2, s[18:19] offset:-1024
	global_load_dword v145, v2, s[18:19] offset:-768
	global_load_dword v146, v2, s[18:19] offset:-512
	global_load_dword v147, v2, s[18:19] offset:-256
	v_readlane_b32 s10, v1, 0
	v_readlane_b32 s11, v104, 0
	v_readlane_b32 s12, v10, 0
	v_readlane_b32 s13, v105, 0
	s_waitcnt vmcnt(32)
	global_load_dword v148, v2, s[18:19]
	global_load_dword v149, v2, s[18:19] offset:256
	global_load_dword v150, v2, s[18:19] offset:512
	global_load_dword v151, v2, s[18:19] offset:768
	global_load_dword v152, v2, s[18:19] offset:1024
	global_load_dword v153, v2, s[18:19] offset:1280
	global_load_dword v154, v2, s[18:19] offset:1536
	global_load_dword v155, v2, s[18:19] offset:1792
	global_load_dword v156, v2, s[18:19] offset:2048
	global_load_dword v157, v2, s[18:19] offset:2304
	global_load_dword v158, v2, s[18:19] offset:2560
	global_load_dword v159, v2, s[18:19] offset:2816
	global_load_dword v160, v2, s[18:19] offset:3072
	global_load_dword v161, v2, s[18:19] offset:3328
	global_load_dword v162, v2, s[18:19] offset:3584
	global_load_dword v163, v2, s[18:19] offset:3840
	s_add_u32 s18, s18, 0x2000
	s_addc_u32 s19, s19, 0
	v_readlane_b32 s14, v11, 0
	v_readlane_b32 s15, v106, 0
	v_pk_fma_f32 v[108:109], v[72:73], s[10:11], v[108:109] op_sel_hi:[0,1,1]
	v_readlane_b32 s16, v12, 0
	v_readlane_b32 s17, v107, 0
	v_pk_fma_f32 v[108:109], v[72:73], s[12:13], v[108:109] op_sel:[1,0,0] op_sel_hi:[1,1,1]
	v_readlane_b32 s10, v1, 1
	v_readlane_b32 s11, v104, 1
	v_pk_fma_f32 v[108:109], v[74:75], s[14:15], v[108:109] op_sel_hi:[0,1,1]
	v_readlane_b32 s12, v10, 1
	v_readlane_b32 s13, v105, 1
	v_pk_fma_f32 v[108:109], v[74:75], s[16:17], v[108:109] op_sel:[1,0,0] op_sel_hi:[1,1,1]
	v_readlane_b32 s14, v11, 1
	v_readlane_b32 s15, v106, 1
	v_pk_fma_f32 v[108:109], v[76:77], s[10:11], v[108:109] op_sel_hi:[0,1,1]
	v_readlane_b32 s16, v12, 1
	v_readlane_b32 s17, v107, 1
	v_pk_fma_f32 v[108:109], v[76:77], s[12:13], v[108:109] op_sel:[1,0,0] op_sel_hi:[1,1,1]
	v_readlane_b32 s10, v1, 2
	v_readlane_b32 s11, v104, 2
	v_pk_fma_f32 v[108:109], v[78:79], s[14:15], v[108:109] op_sel_hi:[0,1,1]
	v_readlane_b32 s12, v10, 2
	v_readlane_b32 s13, v105, 2
	v_pk_fma_f32 v[108:109], v[78:79], s[16:17], v[108:109] op_sel:[1,0,0] op_sel_hi:[1,1,1]
	v_readlane_b32 s14, v11, 2
	v_readlane_b32 s15, v106, 2
	v_pk_fma_f32 v[108:109], v[80:81], s[10:11], v[108:109] op_sel_hi:[0,1,1]
	v_readlane_b32 s16, v12, 2
	v_readlane_b32 s17, v107, 2
	v_pk_fma_f32 v[108:109], v[80:81], s[12:13], v[108:109] op_sel:[1,0,0] op_sel_hi:[1,1,1]
	v_readlane_b32 s10, v1, 3
	v_readlane_b32 s11, v104, 3
	v_pk_fma_f32 v[108:109], v[82:83], s[14:15], v[108:109] op_sel_hi:[0,1,1]
	v_readlane_b32 s12, v10, 3
	v_readlane_b32 s13, v105, 3
	v_pk_fma_f32 v[108:109], v[82:83], s[16:17], v[108:109] op_sel:[1,0,0] op_sel_hi:[1,1,1]
	v_readlane_b32 s14, v11, 3
	v_readlane_b32 s15, v106, 3
	v_pk_fma_f32 v[108:109], v[84:85], s[10:11], v[108:109] op_sel_hi:[0,1,1]
	v_readlane_b32 s16, v12, 3
	v_readlane_b32 s17, v107, 3
	v_pk_fma_f32 v[108:109], v[84:85], s[12:13], v[108:109] op_sel:[1,0,0] op_sel_hi:[1,1,1]
	v_readlane_b32 s10, v1, 4
	v_readlane_b32 s11, v104, 4
	v_pk_fma_f32 v[108:109], v[86:87], s[14:15], v[108:109] op_sel_hi:[0,1,1]
	v_readlane_b32 s12, v10, 4
	v_readlane_b32 s13, v105, 4
	v_pk_fma_f32 v[108:109], v[86:87], s[16:17], v[108:109] op_sel:[1,0,0] op_sel_hi:[1,1,1]
	s_waitcnt vmcnt(32)
; __global__ void __launch_bounds__(512, 2) mega(Args a) {
;     ...
; #pragma unroll 16
;                     for (int jj = 0; jj < 64; ++jj) {
;                         acc += __int_as_float(__builtin_amdgcn_readlane(__float_as_int(h0), jj)) * w2[(jj * 4 + 0) * 64];
;                         acc += __int_as_float(__builtin_amdgcn_readlane(__float_as_int(h1), jj)) * w2[(jj * 4 + 1) * 64];
;                         acc += __int_as_float(__builtin_amdgcn_readlane(__float_as_int(h2), jj)) * w2[(jj * 4 + 2) * 64];
;                         acc += __int_as_float(__builtin_amdgcn_readlane(__float_as_int(h3), jj)) * w2[(jj * 4 + 3) * 64]; }
	global_load_dword v72, v2, s[18:19] offset:-4096
	global_load_dword v73, v2, s[18:19] offset:-3840
	global_load_dword v74, v2, s[18:19] offset:-3584
	global_load_dword v75, v2, s[18:19] offset:-3328
	global_load_dword v76, v2, s[18:19] offset:-3072
	global_load_dword v77, v2, s[18:19] offset:-2816
	global_load_dword v78, v2, s[18:19] offset:-2560
	global_load_dword v79, v2, s[18:19] offset:-2304
	global_load_dword v80, v2, s[18:19] offset:-2048
	global_load_dword v81, v2, s[18:19] offset:-1792
	global_load_dword v82, v2, s[18:19] offset:-1536
	global_load_dword v83, v2, s[18:19] offset:-1280
	global_load_dword v84, v2, s[18:19] offset:-1024
	global_load_dword v85, v2, s[18:19] offset:-768
	global_load_dword v86, v2, s[18:19] offset:-512
	global_load_dword v87, v2, s[18:19] offset:-256
	v_readlane_b32 s14, v11, 4
	v_readlane_b32 s15, v106, 4
	v_pk_fma_f32 v[108:109], v[88:89], s[10:11], v[108:109] op_sel_hi:[0,1,1]
	v_readlane_b32 s16, v12, 4
	v_readlane_b32 s17, v107, 4
	v_pk_fma_f32 v[108:109], v[88:89], s[12:13], v[108:109] op_sel:[1,0,0] op_sel_hi:[1,1,1]
	v_readlane_b32 s10, v1, 5
	v_readlane_b32 s11, v104, 5
	v_pk_fma_f32 v[108:109], v[90:91], s[14:15], v[108:109] op_sel_hi:[0,1,1]
	v_readlane_b32 s12, v10, 5
	v_readlane_b32 s13, v105, 5
	v_pk_fma_f32 v[108:109], v[90:91], s[16:17], v[108:109] op_sel:[1,0,0] op_sel_hi:[1,1,1]
	v_readlane_b32 s14, v11, 5
	v_readlane_b32 s15, v106, 5
	v_pk_fma_f32 v[108:109], v[92:93], s[10:11], v[108:109] op_sel_hi:[0,1,1]
	v_readlane_b32 s16, v12, 5
	v_readlane_b32 s17, v107, 5
	v_pk_fma_f32 v[108:109], v[92:93], s[12:13], v[108:109] op_sel:[1,0,0] op_sel_hi:[1,1,1]
	v_readlane_b32 s10, v1, 6
	v_readlane_b32 s11, v104, 6
	v_pk_fma_f32 v[108:109], v[94:95], s[14:15], v[108:109] op_sel_hi:[0,1,1]
	v_readlane_b32 s12, v10, 6
	v_readlane_b32 s13, v105, 6
	v_pk_fma_f32 v[108:109], v[94:95], s[16:17], v[108:109] op_sel:[1,0,0] op_sel_hi:[1,1,1]
	v_readlane_b32 s14, v11, 6
	v_readlane_b32 s15, v106, 6
	v_pk_fma_f32 v[108:109], v[96:97], s[10:11], v[108:109] op_sel_hi:[0,1,1]
	v_readlane_b32 s16, v12, 6
	v_readlane_b32 s17, v107, 6
	v_pk_fma_f32 v[108:109], v[96:97], s[12:13], v[108:109] op_sel:[1,0,0] op_sel_hi:[1,1,1]
	v_readlane_b32 s10, v1, 7
	v_readlane_b32 s11, v104, 7
	v_pk_fma_f32 v[108:109], v[98:99], s[14:15], v[108:109] op_sel_hi:[0,1,1]
	v_readlane_b32 s12, v10, 7
	v_readlane_b32 s13, v105, 7
	v_pk_fma_f32 v[108:109], v[98:99], s[16:17], v[108:109] op_sel:[1,0,0] op_sel_hi:[1,1,1]
	v_readlane_b32 s14, v11, 7
	v_readlane_b32 s15, v106, 7
	v_pk_fma_f32 v[108:109], v[100:101], s[10:11], v[108:109] op_sel_hi:[0,1,1]
	v_readlane_b32 s16, v12, 7
	v_readlane_b32 s17, v107, 7
	v_pk_fma_f32 v[108:109], v[100:101], s[12:13], v[108:109] op_sel:[1,0,0] op_sel_hi:[1,1,1]
	v_readlane_b32 s10, v1, 8
	v_readlane_b32 s11, v104, 8
	v_pk_fma_f32 v[108:109], v[102:103], s[14:15], v[108:109] op_sel_hi:[0,1,1]
	v_readlane_b32 s12, v10, 8
	v_readlane_b32 s13, v105, 8
	v_pk_fma_f32 v[108:109], v[102:103], s[16:17], v[108:109] op_sel:[1,0,0] op_sel_hi:[1,1,1]
	s_waitcnt vmcnt(32)
	global_load_dword v88, v2, s[18:19]
	global_load_dword v89, v2, s[18:19] offset:256
	global_load_dword v90, v2, s[18:19] offset:512
	global_load_dword v91, v2, s[18:19] offset:768
	global_load_dword v92, v2, s[18:19] offset:1024
	global_load_dword v93, v2, s[18:19] offset:1280
	global_load_dword v94, v2, s[18:19] offset:1536
	global_load_dword v95, v2, s[18:19] offset:1792
	global_load_dword v96, v2, s[18:19] offset:2048
	global_load_dword v97, v2, s[18:19] offset:2304
	global_load_dword v98, v2, s[18:19] offset:2560
	global_load_dword v99, v2, s[18:19] offset:2816
	global_load_dword v100, v2, s[18:19] offset:3072
	global_load_dword v101, v2, s[18:19] offset:3328
	global_load_dword v102, v2, s[18:19] offset:3584
	global_load_dword v103, v2, s[18:19] offset:3840
	s_add_u32 s18, s18, 0x2000
	s_addc_u32 s19, s19, 0
	v_readlane_b32 s14, v11, 8
	v_readlane_b32 s15, v106, 8
	v_pk_fma_f32 v[108:109], v[132:133], s[10:11], v[108:109] op_sel_hi:[0,1,1]
	v_readlane_b32 s16, v12, 8
	v_readlane_b32 s17, v107, 8
	v_pk_fma_f32 v[108:109], v[132:133], s[12:13], v[108:109] op_sel:[1,0,0] op_sel_hi:[1,1,1]
	v_readlane_b32 s10, v1, 9
	v_readlane_b32 s11, v104, 9
	v_pk_fma_f32 v[108:109], v[134:135], s[14:15], v[108:109] op_sel_hi:[0,1,1]
	v_readlane_b32 s12, v10, 9
	v_readlane_b32 s13, v105, 9
	v_pk_fma_f32 v[108:109], v[134:135], s[16:17], v[108:109] op_sel:[1,0,0] op_sel_hi:[1,1,1]
	v_readlane_b32 s14, v11, 9
	v_readlane_b32 s15, v106, 9
	v_pk_fma_f32 v[108:109], v[136:137], s[10:11], v[108:109] op_sel_hi:[0,1,1]
	v_readlane_b32 s16, v12, 9
	v_readlane_b32 s17, v107, 9
	v_pk_fma_f32 v[108:109], v[136:137], s[12:13], v[108:109] op_sel:[1,0,0] op_sel_hi:[1,1,1]
	v_readlane_b32 s10, v1, 10
	v_readlane_b32 s11, v104, 10
	v_pk_fma_f32 v[108:109], v[138:139], s[14:15], v[108:109] op_sel_hi:[0,1,1]
	v_readlane_b32 s12, v10, 10
	v_readlane_b32 s13, v105, 10
	v_pk_fma_f32 v[108:109], v[138:139], s[16:17], v[108:109] op_sel:[1,0,0] op_sel_hi:[1,1,1]
	v_readlane_b32 s14, v11, 10
	v_readlane_b32 s15, v106, 10
	v_pk_fma_f32 v[108:109], v[140:141], s[10:11], v[108:109] op_sel_hi:[0,1,1]
	v_readlane_b32 s16, v12, 10
	v_readlane_b32 s17, v107, 10
	v_pk_fma_f32 v[108:109], v[140:141], s[12:13], v[108:109] op_sel:[1,0,0] op_sel_hi:[1,1,1]
	v_readlane_b32 s10, v1, 11
	v_readlane_b32 s11, v104, 11
	v_pk_fma_f32 v[108:109], v[142:143], s[14:15], v[108:109] op_sel_hi:[0,1,1]
	v_readlane_b32 s12, v10, 11
	v_readlane_b32 s13, v105, 11
	v_pk_fma_f32 v[108:109], v[142:143], s[16:17], v[108:109] op_sel:[1,0,0] op_sel_hi:[1,1,1]
	v_readlane_b32 s14, v11, 11
	v_readlane_b32 s15, v106, 11
	v_pk_fma_f32 v[108:109], v[144:145], s[10:11], v[108:109] op_sel_hi:[0,1,1]
	v_readlane_b32 s16, v12, 11
	v_readlane_b32 s17, v107, 11
	v_pk_fma_f32 v[108:109], v[144:145], s[12:13], v[108:109] op_sel:[1,0,0] op_sel_hi:[1,1,1]
	v_readlane_b32 s10, v1, 12
	v_readlane_b32 s11, v104, 12
	v_pk_fma_f32 v[108:109], v[146:147], s[14:15], v[108:109] op_sel_hi:[0,1,1]
	v_readlane_b32 s12, v10, 12
	v_readlane_b32 s13, v105, 12
	v_pk_fma_f32 v[108:109], v[146:147], s[16:17], v[108:109] op_sel:[1,0,0] op_sel_hi:[1,1,1]
	s_waitcnt vmcnt(32)
; __global__ void __launch_bounds__(512, 2) mega(Args a) {
;     ...
; #pragma unroll 16
;                     for (int jj = 0; jj < 64; ++jj) {
;                         acc += __int_as_float(__builtin_amdgcn_readlane(__float_as_int(h0), jj)) * w2[(jj * 4 + 0) * 64];
;                         acc += __int_as_float(__builtin_amdgcn_readlane(__float_as_int(h1), jj)) * w2[(jj * 4 + 1) * 64];
;                         acc += __int_as_float(__builtin_amdgcn_readlane(__float_as_int(h2), jj)) * w2[(jj * 4 + 2) * 64];
;                         acc += __int_as_float(__builtin_amdgcn_readlane(__float_as_int(h3), jj)) * w2[(jj * 4 + 3) * 64]; }
	global_load_dword v132, v2, s[18:19] offset:-4096
	global_load_dword v133, v2, s[18:19] offset:-3840
	global_load_dword v134, v2, s[18:19] offset:-3584
	global_load_dword v135, v2, s[18:19] offset:-3328
	global_load_dword v136, v2, s[18:19] offset:-3072
	global_load_dword v137, v2, s[18:19] offset:-2816
	global_load_dword v138, v2, s[18:19] offset:-2560
	global_load_dword v139, v2, s[18:19] offset:-2304
	global_load_dword v140, v2, s[18:19] offset:-2048
	global_load_dword v141, v2, s[18:19] offset:-1792
	global_load_dword v142, v2, s[18:19] offset:-1536
	global_load_dword v143, v2, s[18:19] offset:-1280
	global_load_dword v144, v2, s[18:19] offset:-1024
	global_load_dword v145, v2, s[18:19] offset:-768
	global_load_dword v146, v2, s[18:19] offset:-512
	global_load_dword v147, v2, s[18:19] offset:-256
	v_readlane_b32 s14, v11, 12
	v_readlane_b32 s15, v106, 12
	v_pk_fma_f32 v[108:109], v[148:149], s[10:11], v[108:109] op_sel_hi:[0,1,1]
	v_readlane_b32 s16, v12, 12
	v_readlane_b32 s17, v107, 12
	v_pk_fma_f32 v[108:109], v[148:149], s[12:13], v[108:109] op_sel:[1,0,0] op_sel_hi:[1,1,1]
	v_readlane_b32 s10, v1, 13
	v_readlane_b32 s11, v104, 13
	v_pk_fma_f32 v[108:109], v[150:151], s[14:15], v[108:109] op_sel_hi:[0,1,1]
	v_readlane_b32 s12, v10, 13
	v_readlane_b32 s13, v105, 13
	v_pk_fma_f32 v[108:109], v[150:151], s[16:17], v[108:109] op_sel:[1,0,0] op_sel_hi:[1,1,1]
	v_readlane_b32 s14, v11, 13
	v_readlane_b32 s15, v106, 13
	v_pk_fma_f32 v[108:109], v[152:153], s[10:11], v[108:109] op_sel_hi:[0,1,1]
	v_readlane_b32 s16, v12, 13
	v_readlane_b32 s17, v107, 13
	v_pk_fma_f32 v[108:109], v[152:153], s[12:13], v[108:109] op_sel:[1,0,0] op_sel_hi:[1,1,1]
	v_readlane_b32 s10, v1, 14
	v_readlane_b32 s11, v104, 14
	v_pk_fma_f32 v[108:109], v[154:155], s[14:15], v[108:109] op_sel_hi:[0,1,1]
	v_readlane_b32 s12, v10, 14
	v_readlane_b32 s13, v105, 14
	v_pk_fma_f32 v[108:109], v[154:155], s[16:17], v[108:109] op_sel:[1,0,0] op_sel_hi:[1,1,1]
	v_readlane_b32 s14, v11, 14
	v_readlane_b32 s15, v106, 14
	v_pk_fma_f32 v[108:109], v[156:157], s[10:11], v[108:109] op_sel_hi:[0,1,1]
	v_readlane_b32 s16, v12, 14
	v_readlane_b32 s17, v107, 14
	v_pk_fma_f32 v[108:109], v[156:157], s[12:13], v[108:109] op_sel:[1,0,0] op_sel_hi:[1,1,1]
	v_readlane_b32 s10, v1, 15
	v_readlane_b32 s11, v104, 15
	v_pk_fma_f32 v[108:109], v[158:159], s[14:15], v[108:109] op_sel_hi:[0,1,1]
	v_readlane_b32 s12, v10, 15
	v_readlane_b32 s13, v105, 15
	v_pk_fma_f32 v[108:109], v[158:159], s[16:17], v[108:109] op_sel:[1,0,0] op_sel_hi:[1,1,1]
	v_readlane_b32 s14, v11, 15
	v_readlane_b32 s15, v106, 15
	v_pk_fma_f32 v[108:109], v[160:161], s[10:11], v[108:109] op_sel_hi:[0,1,1]
	v_readlane_b32 s16, v12, 15
	v_readlane_b32 s17, v107, 15
	v_pk_fma_f32 v[108:109], v[160:161], s[12:13], v[108:109] op_sel:[1,0,0] op_sel_hi:[1,1,1]
	v_readlane_b32 s10, v1, 16
	v_readlane_b32 s11, v104, 16
	v_pk_fma_f32 v[108:109], v[162:163], s[14:15], v[108:109] op_sel_hi:[0,1,1]
	v_readlane_b32 s12, v10, 16
	v_readlane_b32 s13, v105, 16
	v_pk_fma_f32 v[108:109], v[162:163], s[16:17], v[108:109] op_sel:[1,0,0] op_sel_hi:[1,1,1]
	s_waitcnt vmcnt(32)
	global_load_dword v148, v2, s[18:19]
	global_load_dword v149, v2, s[18:19] offset:256
	global_load_dword v150, v2, s[18:19] offset:512
	global_load_dword v151, v2, s[18:19] offset:768
	global_load_dword v152, v2, s[18:19] offset:1024
	global_load_dword v153, v2, s[18:19] offset:1280
	global_load_dword v154, v2, s[18:19] offset:1536
	global_load_dword v155, v2, s[18:19] offset:1792
	global_load_dword v156, v2, s[18:19] offset:2048
	global_load_dword v157, v2, s[18:19] offset:2304
	global_load_dword v158, v2, s[18:19] offset:2560
	global_load_dword v159, v2, s[18:19] offset:2816
	global_load_dword v160, v2, s[18:19] offset:3072
	global_load_dword v161, v2, s[18:19] offset:3328
	global_load_dword v162, v2, s[18:19] offset:3584
	global_load_dword v163, v2, s[18:19] offset:3840
	s_add_u32 s18, s18, 0x2000
	s_addc_u32 s19, s19, 0
	v_readlane_b32 s14, v11, 16
	v_readlane_b32 s15, v106, 16
	v_pk_fma_f32 v[108:109], v[72:73], s[10:11], v[108:109] op_sel_hi:[0,1,1]
	v_readlane_b32 s16, v12, 16
	v_readlane_b32 s17, v107, 16
	v_pk_fma_f32 v[108:109], v[72:73], s[12:13], v[108:109] op_sel:[1,0,0] op_sel_hi:[1,1,1]
	v_readlane_b32 s10, v1, 17
	v_readlane_b32 s11, v104, 17
	v_pk_fma_f32 v[108:109], v[74:75], s[14:15], v[108:109] op_sel_hi:[0,1,1]
	v_readlane_b32 s12, v10, 17
	v_readlane_b32 s13, v105, 17
	v_pk_fma_f32 v[108:109], v[74:75], s[16:17], v[108:109] op_sel:[1,0,0] op_sel_hi:[1,1,1]
	v_readlane_b32 s14, v11, 17
	v_readlane_b32 s15, v106, 17
	v_pk_fma_f32 v[108:109], v[76:77], s[10:11], v[108:109] op_sel_hi:[0,1,1]
	v_readlane_b32 s16, v12, 17
	v_readlane_b32 s17, v107, 17
	v_pk_fma_f32 v[108:109], v[76:77], s[12:13], v[108:109] op_sel:[1,0,0] op_sel_hi:[1,1,1]
	v_readlane_b32 s10, v1, 18
	v_readlane_b32 s11, v104, 18
	v_pk_fma_f32 v[108:109], v[78:79], s[14:15], v[108:109] op_sel_hi:[0,1,1]
	v_readlane_b32 s12, v10, 18
	v_readlane_b32 s13, v105, 18
	v_pk_fma_f32 v[108:109], v[78:79], s[16:17], v[108:109] op_sel:[1,0,0] op_sel_hi:[1,1,1]
	v_readlane_b32 s14, v11, 18
	v_readlane_b32 s15, v106, 18
	v_pk_fma_f32 v[108:109], v[80:81], s[10:11], v[108:109] op_sel_hi:[0,1,1]
	v_readlane_b32 s16, v12, 18
	v_readlane_b32 s17, v107, 18
	v_pk_fma_f32 v[108:109], v[80:81], s[12:13], v[108:109] op_sel:[1,0,0] op_sel_hi:[1,1,1]
	v_readlane_b32 s10, v1, 19
	v_readlane_b32 s11, v104, 19
	v_pk_fma_f32 v[108:109], v[82:83], s[14:15], v[108:109] op_sel_hi:[0,1,1]
	v_readlane_b32 s12, v10, 19
	v_readlane_b32 s13, v105, 19
	v_pk_fma_f32 v[108:109], v[82:83], s[16:17], v[108:109] op_sel:[1,0,0] op_sel_hi:[1,1,1]
	v_readlane_b32 s14, v11, 19
	v_readlane_b32 s15, v106, 19
	v_pk_fma_f32 v[108:109], v[84:85], s[10:11], v[108:109] op_sel_hi:[0,1,1]
	v_readlane_b32 s16, v12, 19
	v_readlane_b32 s17, v107, 19
	v_pk_fma_f32 v[108:109], v[84:85], s[12:13], v[108:109] op_sel:[1,0,0] op_sel_hi:[1,1,1]
	v_readlane_b32 s10, v1, 20
	v_readlane_b32 s11, v104, 20
	v_pk_fma_f32 v[108:109], v[86:87], s[14:15], v[108:109] op_sel_hi:[0,1,1]
	v_readlane_b32 s12, v10, 20
	v_readlane_b32 s13, v105, 20
	v_pk_fma_f32 v[108:109], v[86:87], s[16:17], v[108:109] op_sel:[1,0,0] op_sel_hi:[1,1,1]
	s_waitcnt vmcnt(32)
; __global__ void __launch_bounds__(512, 2) mega(Args a) {
;     ...
; #pragma unroll 16
;                     for (int jj = 0; jj < 64; ++jj) {
;                         acc += __int_as_float(__builtin_amdgcn_readlane(__float_as_int(h0), jj)) * w2[(jj * 4 + 0) * 64];
;                         acc += __int_as_float(__builtin_amdgcn_readlane(__float_as_int(h1), jj)) * w2[(jj * 4 + 1) * 64];
;                         acc += __int_as_float(__builtin_amdgcn_readlane(__float_as_int(h2), jj)) * w2[(jj * 4 + 2) * 64];
;                         acc += __int_as_float(__builtin_amdgcn_readlane(__float_as_int(h3), jj)) * w2[(jj * 4 + 3) * 64]; }
	global_load_dword v72, v2, s[18:19] offset:-4096
	global_load_dword v73, v2, s[18:19] offset:-3840
	global_load_dword v74, v2, s[18:19] offset:-3584
	global_load_dword v75, v2, s[18:19] offset:-3328
	global_load_dword v76, v2, s[18:19] offset:-3072
	global_load_dword v77, v2, s[18:19] offset:-2816
	global_load_dword v78, v2, s[18:19] offset:-2560
	global_load_dword v79, v2, s[18:19] offset:-2304
	global_load_dword v80, v2, s[18:19] offset:-2048
	global_load_dword v81, v2, s[18:19] offset:-1792
	global_load_dword v82, v2, s[18:19] offset:-1536
	global_load_dword v83, v2, s[18:19] offset:-1280
	global_load_dword v84, v2, s[18:19] offset:-1024
	global_load_dword v85, v2, s[18:19] offset:-768
	global_load_dword v86, v2, s[18:19] offset:-512
	global_load_dword v87, v2, s[18:19] offset:-256
	v_readlane_b32 s14, v11, 20
	v_readlane_b32 s15, v106, 20
	v_pk_fma_f32 v[108:109], v[88:89], s[10:11], v[108:109] op_sel_hi:[0,1,1]
	v_readlane_b32 s16, v12, 20
	v_readlane_b32 s17, v107, 20
	v_pk_fma_f32 v[108:109], v[88:89], s[12:13], v[108:109] op_sel:[1,0,0] op_sel_hi:[1,1,1]
	v_readlane_b32 s10, v1, 21
	v_readlane_b32 s11, v104, 21
	v_pk_fma_f32 v[108:109], v[90:91], s[14:15], v[108:109] op_sel_hi:[0,1,1]
	v_readlane_b32 s12, v10, 21
	v_readlane_b32 s13, v105, 21
	v_pk_fma_f32 v[108:109], v[90:91], s[16:17], v[108:109] op_sel:[1,0,0] op_sel_hi:[1,1,1]
	v_readlane_b32 s14, v11, 21
	v_readlane_b32 s15, v106, 21
	v_pk_fma_f32 v[108:109], v[92:93], s[10:11], v[108:109] op_sel_hi:[0,1,1]
	v_readlane_b32 s16, v12, 21
	v_readlane_b32 s17, v107, 21
	v_pk_fma_f32 v[108:109], v[92:93], s[12:13], v[108:109] op_sel:[1,0,0] op_sel_hi:[1,1,1]
	v_readlane_b32 s10, v1, 22
	v_readlane_b32 s11, v104, 22
	v_pk_fma_f32 v[108:109], v[94:95], s[14:15], v[108:109] op_sel_hi:[0,1,1]
	v_readlane_b32 s12, v10, 22
	v_readlane_b32 s13, v105, 22
	v_pk_fma_f32 v[108:109], v[94:95], s[16:17], v[108:109] op_sel:[1,0,0] op_sel_hi:[1,1,1]
	v_readlane_b32 s14, v11, 22
	v_readlane_b32 s15, v106, 22
	v_pk_fma_f32 v[108:109], v[96:97], s[10:11], v[108:109] op_sel_hi:[0,1,1]
	v_readlane_b32 s16, v12, 22
	v_readlane_b32 s17, v107, 22
	v_pk_fma_f32 v[108:109], v[96:97], s[12:13], v[108:109] op_sel:[1,0,0] op_sel_hi:[1,1,1]
	v_readlane_b32 s10, v1, 23
	v_readlane_b32 s11, v104, 23
	v_pk_fma_f32 v[108:109], v[98:99], s[14:15], v[108:109] op_sel_hi:[0,1,1]
	v_readlane_b32 s12, v10, 23
	v_readlane_b32 s13, v105, 23
	v_pk_fma_f32 v[108:109], v[98:99], s[16:17], v[108:109] op_sel:[1,0,0] op_sel_hi:[1,1,1]
	v_readlane_b32 s14, v11, 23
	v_readlane_b32 s15, v106, 23
	v_pk_fma_f32 v[108:109], v[100:101], s[10:11], v[108:109] op_sel_hi:[0,1,1]
	v_readlane_b32 s16, v12, 23
	v_readlane_b32 s17, v107, 23
	v_pk_fma_f32 v[108:109], v[100:101], s[12:13], v[108:109] op_sel:[1,0,0] op_sel_hi:[1,1,1]
	v_readlane_b32 s10, v1, 24
	v_readlane_b32 s11, v104, 24
	v_pk_fma_f32 v[108:109], v[102:103], s[14:15], v[108:109] op_sel_hi:[0,1,1]
	v_readlane_b32 s12, v10, 24
	v_readlane_b32 s13, v105, 24
	v_pk_fma_f32 v[108:109], v[102:103], s[16:17], v[108:109] op_sel:[1,0,0] op_sel_hi:[1,1,1]
	s_waitcnt vmcnt(32)
	global_load_dword v88, v2, s[18:19]
	global_load_dword v89, v2, s[18:19] offset:256
	global_load_dword v90, v2, s[18:19] offset:512
	global_load_dword v91, v2, s[18:19] offset:768
	global_load_dword v92, v2, s[18:19] offset:1024
	global_load_dword v93, v2, s[18:19] offset:1280
	global_load_dword v94, v2, s[18:19] offset:1536
	global_load_dword v95, v2, s[18:19] offset:1792
	global_load_dword v96, v2, s[18:19] offset:2048
	global_load_dword v97, v2, s[18:19] offset:2304
	global_load_dword v98, v2, s[18:19] offset:2560
	global_load_dword v99, v2, s[18:19] offset:2816
	global_load_dword v100, v2, s[18:19] offset:3072
	global_load_dword v101, v2, s[18:19] offset:3328
	global_load_dword v102, v2, s[18:19] offset:3584
	global_load_dword v103, v2, s[18:19] offset:3840
	s_add_u32 s18, s18, 0x2000
	s_addc_u32 s19, s19, 0
	v_readlane_b32 s14, v11, 24
	v_readlane_b32 s15, v106, 24
	v_pk_fma_f32 v[108:109], v[132:133], s[10:11], v[108:109] op_sel_hi:[0,1,1]
	v_readlane_b32 s16, v12, 24
	v_readlane_b32 s17, v107, 24
	v_pk_fma_f32 v[108:109], v[132:133], s[12:13], v[108:109] op_sel:[1,0,0] op_sel_hi:[1,1,1]
	v_readlane_b32 s10, v1, 25
	v_readlane_b32 s11, v104, 25
	v_pk_fma_f32 v[108:109], v[134:135], s[14:15], v[108:109] op_sel_hi:[0,1,1]
	v_readlane_b32 s12, v10, 25
	v_readlane_b32 s13, v105, 25
	v_pk_fma_f32 v[108:109], v[134:135], s[16:17], v[108:109] op_sel:[1,0,0] op_sel_hi:[1,1,1]
	v_readlane_b32 s14, v11, 25
	v_readlane_b32 s15, v106, 25
	v_pk_fma_f32 v[108:109], v[136:137], s[10:11], v[108:109] op_sel_hi:[0,1,1]
	v_readlane_b32 s16, v12, 25
	v_readlane_b32 s17, v107, 25
	v_pk_fma_f32 v[108:109], v[136:137], s[12:13], v[108:109] op_sel:[1,0,0] op_sel_hi:[1,1,1]
	v_readlane_b32 s10, v1, 26
	v_readlane_b32 s11, v104, 26
	v_pk_fma_f32 v[108:109], v[138:139], s[14:15], v[108:109] op_sel_hi:[0,1,1]
	v_readlane_b32 s12, v10, 26
	v_readlane_b32 s13, v105, 26
	v_pk_fma_f32 v[108:109], v[138:139], s[16:17], v[108:109] op_sel:[1,0,0] op_sel_hi:[1,1,1]
	v_readlane_b32 s14, v11, 26
	v_readlane_b32 s15, v106, 26
	v_pk_fma_f32 v[108:109], v[140:141], s[10:11], v[108:109] op_sel_hi:[0,1,1]
	v_readlane_b32 s16, v12, 26
	v_readlane_b32 s17, v107, 26
	v_pk_fma_f32 v[108:109], v[140:141], s[12:13], v[108:109] op_sel:[1,0,0] op_sel_hi:[1,1,1]
	v_readlane_b32 s10, v1, 27
	v_readlane_b32 s11, v104, 27
	v_pk_fma_f32 v[108:109], v[142:143], s[14:15], v[108:109] op_sel_hi:[0,1,1]
	v_readlane_b32 s12, v10, 27
	v_readlane_b32 s13, v105, 27
	v_pk_fma_f32 v[108:109], v[142:143], s[16:17], v[108:109] op_sel:[1,0,0] op_sel_hi:[1,1,1]
	v_readlane_b32 s14, v11, 27
	v_readlane_b32 s15, v106, 27
	v_pk_fma_f32 v[108:109], v[144:145], s[10:11], v[108:109] op_sel_hi:[0,1,1]
	v_readlane_b32 s16, v12, 27
	v_readlane_b32 s17, v107, 27
	v_pk_fma_f32 v[108:109], v[144:145], s[12:13], v[108:109] op_sel:[1,0,0] op_sel_hi:[1,1,1]
	v_readlane_b32 s10, v1, 28
	v_readlane_b32 s11, v104, 28
	v_pk_fma_f32 v[108:109], v[146:147], s[14:15], v[108:109] op_sel_hi:[0,1,1]
	v_readlane_b32 s12, v10, 28
	v_readlane_b32 s13, v105, 28
	v_pk_fma_f32 v[108:109], v[146:147], s[16:17], v[108:109] op_sel:[1,0,0] op_sel_hi:[1,1,1]
	s_waitcnt vmcnt(32)
; __global__ void __launch_bounds__(512, 2) mega(Args a) {
;     ...
; #pragma unroll 16
;                     for (int jj = 0; jj < 64; ++jj) {
;                         acc += __int_as_float(__builtin_amdgcn_readlane(__float_as_int(h0), jj)) * w2[(jj * 4 + 0) * 64];
;                         acc += __int_as_float(__builtin_amdgcn_readlane(__float_as_int(h1), jj)) * w2[(jj * 4 + 1) * 64];
;                         acc += __int_as_float(__builtin_amdgcn_readlane(__float_as_int(h2), jj)) * w2[(jj * 4 + 2) * 64];
;                         acc += __int_as_float(__builtin_amdgcn_readlane(__float_as_int(h3), jj)) * w2[(jj * 4 + 3) * 64]; }
	global_load_dword v132, v2, s[18:19] offset:-4096
	global_load_dword v133, v2, s[18:19] offset:-3840
	global_load_dword v134, v2, s[18:19] offset:-3584
	global_load_dword v135, v2, s[18:19] offset:-3328
	global_load_dword v136, v2, s[18:19] offset:-3072
	global_load_dword v137, v2, s[18:19] offset:-2816
	global_load_dword v138, v2, s[18:19] offset:-2560
	global_load_dword v139, v2, s[18:19] offset:-2304
	global_load_dword v140, v2, s[18:19] offset:-2048
	global_load_dword v141, v2, s[18:19] offset:-1792
	global_load_dword v142, v2, s[18:19] offset:-1536
	global_load_dword v143, v2, s[18:19] offset:-1280
	global_load_dword v144, v2, s[18:19] offset:-1024
	global_load_dword v145, v2, s[18:19] offset:-768
	global_load_dword v146, v2, s[18:19] offset:-512
	global_load_dword v147, v2, s[18:19] offset:-256
	v_readlane_b32 s14, v11, 28
	v_readlane_b32 s15, v106, 28
	v_pk_fma_f32 v[108:109], v[148:149], s[10:11], v[108:109] op_sel_hi:[0,1,1]
	v_readlane_b32 s16, v12, 28
	v_readlane_b32 s17, v107, 28
	v_pk_fma_f32 v[108:109], v[148:149], s[12:13], v[108:109] op_sel:[1,0,0] op_sel_hi:[1,1,1]
	v_readlane_b32 s10, v1, 29
	v_readlane_b32 s11, v104, 29
	v_pk_fma_f32 v[108:109], v[150:151], s[14:15], v[108:109] op_sel_hi:[0,1,1]
	v_readlane_b32 s12, v10, 29
	v_readlane_b32 s13, v105, 29
	v_pk_fma_f32 v[108:109], v[150:151], s[16:17], v[108:109] op_sel:[1,0,0] op_sel_hi:[1,1,1]
	v_readlane_b32 s14, v11, 29
	v_readlane_b32 s15, v106, 29
	v_pk_fma_f32 v[108:109], v[152:153], s[10:11], v[108:109] op_sel_hi:[0,1,1]
	v_readlane_b32 s16, v12, 29
	v_readlane_b32 s17, v107, 29
	v_pk_fma_f32 v[108:109], v[152:153], s[12:13], v[108:109] op_sel:[1,0,0] op_sel_hi:[1,1,1]
	v_readlane_b32 s10, v1, 30
	v_readlane_b32 s11, v104, 30
	v_pk_fma_f32 v[108:109], v[154:155], s[14:15], v[108:109] op_sel_hi:[0,1,1]
	v_readlane_b32 s12, v10, 30
	v_readlane_b32 s13, v105, 30
	v_pk_fma_f32 v[108:109], v[154:155], s[16:17], v[108:109] op_sel:[1,0,0] op_sel_hi:[1,1,1]
	v_readlane_b32 s14, v11, 30
	v_readlane_b32 s15, v106, 30
	v_pk_fma_f32 v[108:109], v[156:157], s[10:11], v[108:109] op_sel_hi:[0,1,1]
	v_readlane_b32 s16, v12, 30
	v_readlane_b32 s17, v107, 30
	v_pk_fma_f32 v[108:109], v[156:157], s[12:13], v[108:109] op_sel:[1,0,0] op_sel_hi:[1,1,1]
	v_readlane_b32 s10, v1, 31
	v_readlane_b32 s11, v104, 31
	v_pk_fma_f32 v[108:109], v[158:159], s[14:15], v[108:109] op_sel_hi:[0,1,1]
	v_readlane_b32 s12, v10, 31
	v_readlane_b32 s13, v105, 31
	v_pk_fma_f32 v[108:109], v[158:159], s[16:17], v[108:109] op_sel:[1,0,0] op_sel_hi:[1,1,1]
	v_readlane_b32 s14, v11, 31
	v_readlane_b32 s15, v106, 31
	v_pk_fma_f32 v[108:109], v[160:161], s[10:11], v[108:109] op_sel_hi:[0,1,1]
	v_readlane_b32 s16, v12, 31
	v_readlane_b32 s17, v107, 31
	v_pk_fma_f32 v[108:109], v[160:161], s[12:13], v[108:109] op_sel:[1,0,0] op_sel_hi:[1,1,1]
	v_readlane_b32 s10, v1, 32
	v_readlane_b32 s11, v104, 32
	v_pk_fma_f32 v[108:109], v[162:163], s[14:15], v[108:109] op_sel_hi:[0,1,1]
	v_readlane_b32 s12, v10, 32
	v_readlane_b32 s13, v105, 32
	v_pk_fma_f32 v[108:109], v[162:163], s[16:17], v[108:109] op_sel:[1,0,0] op_sel_hi:[1,1,1]
	s_waitcnt vmcnt(32)
	global_load_dword v148, v2, s[18:19]
	global_load_dword v149, v2, s[18:19] offset:256
	global_load_dword v150, v2, s[18:19] offset:512
	global_load_dword v151, v2, s[18:19] offset:768
	global_load_dword v152, v2, s[18:19] offset:1024
	global_load_dword v153, v2, s[18:19] offset:1280
	global_load_dword v154, v2, s[18:19] offset:1536
	global_load_dword v155, v2, s[18:19] offset:1792
	global_load_dword v156, v2, s[18:19] offset:2048
	global_load_dword v157, v2, s[18:19] offset:2304
	global_load_dword v158, v2, s[18:19] offset:2560
	global_load_dword v159, v2, s[18:19] offset:2816
	global_load_dword v160, v2, s[18:19] offset:3072
	global_load_dword v161, v2, s[18:19] offset:3328
	global_load_dword v162, v2, s[18:19] offset:3584
	global_load_dword v163, v2, s[18:19] offset:3840
	s_add_u32 s18, s18, 0x2000
	s_addc_u32 s19, s19, 0
	v_readlane_b32 s14, v11, 32
	v_readlane_b32 s15, v106, 32
	v_pk_fma_f32 v[108:109], v[72:73], s[10:11], v[108:109] op_sel_hi:[0,1,1]
	v_readlane_b32 s16, v12, 32
	v_readlane_b32 s17, v107, 32
	v_pk_fma_f32 v[108:109], v[72:73], s[12:13], v[108:109] op_sel:[1,0,0] op_sel_hi:[1,1,1]
	v_readlane_b32 s10, v1, 33
	v_readlane_b32 s11, v104, 33
	v_pk_fma_f32 v[108:109], v[74:75], s[14:15], v[108:109] op_sel_hi:[0,1,1]
	v_readlane_b32 s12, v10, 33
	v_readlane_b32 s13, v105, 33
	v_pk_fma_f32 v[108:109], v[74:75], s[16:17], v[108:109] op_sel:[1,0,0] op_sel_hi:[1,1,1]
	v_readlane_b32 s14, v11, 33
	v_readlane_b32 s15, v106, 33
	v_pk_fma_f32 v[108:109], v[76:77], s[10:11], v[108:109] op_sel_hi:[0,1,1]
	v_readlane_b32 s16, v12, 33
	v_readlane_b32 s17, v107, 33
	v_pk_fma_f32 v[108:109], v[76:77], s[12:13], v[108:109] op_sel:[1,0,0] op_sel_hi:[1,1,1]
	v_readlane_b32 s10, v1, 34
	v_readlane_b32 s11, v104, 34
	v_pk_fma_f32 v[108:109], v[78:79], s[14:15], v[108:109] op_sel_hi:[0,1,1]
	v_readlane_b32 s12, v10, 34
	v_readlane_b32 s13, v105, 34
	v_pk_fma_f32 v[108:109], v[78:79], s[16:17], v[108:109] op_sel:[1,0,0] op_sel_hi:[1,1,1]
	v_readlane_b32 s14, v11, 34
	v_readlane_b32 s15, v106, 34
	v_pk_fma_f32 v[108:109], v[80:81], s[10:11], v[108:109] op_sel_hi:[0,1,1]
	v_readlane_b32 s16, v12, 34
	v_readlane_b32 s17, v107, 34
	v_pk_fma_f32 v[108:109], v[80:81], s[12:13], v[108:109] op_sel:[1,0,0] op_sel_hi:[1,1,1]
	v_readlane_b32 s10, v1, 35
	v_readlane_b32 s11, v104, 35
	v_pk_fma_f32 v[108:109], v[82:83], s[14:15], v[108:109] op_sel_hi:[0,1,1]
	v_readlane_b32 s12, v10, 35
	v_readlane_b32 s13, v105, 35
	v_pk_fma_f32 v[108:109], v[82:83], s[16:17], v[108:109] op_sel:[1,0,0] op_sel_hi:[1,1,1]
	v_readlane_b32 s14, v11, 35
	v_readlane_b32 s15, v106, 35
	v_pk_fma_f32 v[108:109], v[84:85], s[10:11], v[108:109] op_sel_hi:[0,1,1]
	v_readlane_b32 s16, v12, 35
	v_readlane_b32 s17, v107, 35
	v_pk_fma_f32 v[108:109], v[84:85], s[12:13], v[108:109] op_sel:[1,0,0] op_sel_hi:[1,1,1]
	v_readlane_b32 s10, v1, 36
	v_readlane_b32 s11, v104, 36
	v_pk_fma_f32 v[108:109], v[86:87], s[14:15], v[108:109] op_sel_hi:[0,1,1]
	v_readlane_b32 s12, v10, 36
	v_readlane_b32 s13, v105, 36
	v_pk_fma_f32 v[108:109], v[86:87], s[16:17], v[108:109] op_sel:[1,0,0] op_sel_hi:[1,1,1]
	s_waitcnt vmcnt(32)
; __global__ void __launch_bounds__(512, 2) mega(Args a) {
;     ...
; #pragma unroll 16
;                     for (int jj = 0; jj < 64; ++jj) {
;                         acc += __int_as_float(__builtin_amdgcn_readlane(__float_as_int(h0), jj)) * w2[(jj * 4 + 0) * 64];
;                         acc += __int_as_float(__builtin_amdgcn_readlane(__float_as_int(h1), jj)) * w2[(jj * 4 + 1) * 64];
;                         acc += __int_as_float(__builtin_amdgcn_readlane(__float_as_int(h2), jj)) * w2[(jj * 4 + 2) * 64];
;                         acc += __int_as_float(__builtin_amdgcn_readlane(__float_as_int(h3), jj)) * w2[(jj * 4 + 3) * 64]; }
	global_load_dword v72, v2, s[18:19] offset:-4096
	global_load_dword v73, v2, s[18:19] offset:-3840
	global_load_dword v74, v2, s[18:19] offset:-3584
	global_load_dword v75, v2, s[18:19] offset:-3328
	global_load_dword v76, v2, s[18:19] offset:-3072
	global_load_dword v77, v2, s[18:19] offset:-2816
	global_load_dword v78, v2, s[18:19] offset:-2560
	global_load_dword v79, v2, s[18:19] offset:-2304
	global_load_dword v80, v2, s[18:19] offset:-2048
	global_load_dword v81, v2, s[18:19] offset:-1792
	global_load_dword v82, v2, s[18:19] offset:-1536
	global_load_dword v83, v2, s[18:19] offset:-1280
	global_load_dword v84, v2, s[18:19] offset:-1024
	global_load_dword v85, v2, s[18:19] offset:-768
	global_load_dword v86, v2, s[18:19] offset:-512
	global_load_dword v87, v2, s[18:19] offset:-256
	v_readlane_b32 s14, v11, 36
	v_readlane_b32 s15, v106, 36
	v_pk_fma_f32 v[108:109], v[88:89], s[10:11], v[108:109] op_sel_hi:[0,1,1]
	v_readlane_b32 s16, v12, 36
	v_readlane_b32 s17, v107, 36
	v_pk_fma_f32 v[108:109], v[88:89], s[12:13], v[108:109] op_sel:[1,0,0] op_sel_hi:[1,1,1]
	v_readlane_b32 s10, v1, 37
	v_readlane_b32 s11, v104, 37
	v_pk_fma_f32 v[108:109], v[90:91], s[14:15], v[108:109] op_sel_hi:[0,1,1]
	v_readlane_b32 s12, v10, 37
	v_readlane_b32 s13, v105, 37
	v_pk_fma_f32 v[108:109], v[90:91], s[16:17], v[108:109] op_sel:[1,0,0] op_sel_hi:[1,1,1]
	v_readlane_b32 s14, v11, 37
	v_readlane_b32 s15, v106, 37
	v_pk_fma_f32 v[108:109], v[92:93], s[10:11], v[108:109] op_sel_hi:[0,1,1]
	v_readlane_b32 s16, v12, 37
	v_readlane_b32 s17, v107, 37
	v_pk_fma_f32 v[108:109], v[92:93], s[12:13], v[108:109] op_sel:[1,0,0] op_sel_hi:[1,1,1]
	v_readlane_b32 s10, v1, 38
	v_readlane_b32 s11, v104, 38
	v_pk_fma_f32 v[108:109], v[94:95], s[14:15], v[108:109] op_sel_hi:[0,1,1]
	v_readlane_b32 s12, v10, 38
	v_readlane_b32 s13, v105, 38
	v_pk_fma_f32 v[108:109], v[94:95], s[16:17], v[108:109] op_sel:[1,0,0] op_sel_hi:[1,1,1]
	v_readlane_b32 s14, v11, 38
	v_readlane_b32 s15, v106, 38
	v_pk_fma_f32 v[108:109], v[96:97], s[10:11], v[108:109] op_sel_hi:[0,1,1]
	v_readlane_b32 s16, v12, 38
	v_readlane_b32 s17, v107, 38
	v_pk_fma_f32 v[108:109], v[96:97], s[12:13], v[108:109] op_sel:[1,0,0] op_sel_hi:[1,1,1]
	v_readlane_b32 s10, v1, 39
	v_readlane_b32 s11, v104, 39
	v_pk_fma_f32 v[108:109], v[98:99], s[14:15], v[108:109] op_sel_hi:[0,1,1]
	v_readlane_b32 s12, v10, 39
	v_readlane_b32 s13, v105, 39
	v_pk_fma_f32 v[108:109], v[98:99], s[16:17], v[108:109] op_sel:[1,0,0] op_sel_hi:[1,1,1]
	v_readlane_b32 s14, v11, 39
	v_readlane_b32 s15, v106, 39
	v_pk_fma_f32 v[108:109], v[100:101], s[10:11], v[108:109] op_sel_hi:[0,1,1]
	v_readlane_b32 s16, v12, 39
	v_readlane_b32 s17, v107, 39
	v_pk_fma_f32 v[108:109], v[100:101], s[12:13], v[108:109] op_sel:[1,0,0] op_sel_hi:[1,1,1]
	v_readlane_b32 s10, v1, 40
	v_readlane_b32 s11, v104, 40
	v_pk_fma_f32 v[108:109], v[102:103], s[14:15], v[108:109] op_sel_hi:[0,1,1]
	v_readlane_b32 s12, v10, 40
	v_readlane_b32 s13, v105, 40
	v_pk_fma_f32 v[108:109], v[102:103], s[16:17], v[108:109] op_sel:[1,0,0] op_sel_hi:[1,1,1]
	s_waitcnt vmcnt(32)
	global_load_dword v88, v2, s[18:19]
	global_load_dword v89, v2, s[18:19] offset:256
	global_load_dword v90, v2, s[18:19] offset:512
	global_load_dword v91, v2, s[18:19] offset:768
	global_load_dword v92, v2, s[18:19] offset:1024
	global_load_dword v93, v2, s[18:19] offset:1280
	global_load_dword v94, v2, s[18:19] offset:1536
	global_load_dword v95, v2, s[18:19] offset:1792
	global_load_dword v96, v2, s[18:19] offset:2048
	global_load_dword v97, v2, s[18:19] offset:2304
	global_load_dword v98, v2, s[18:19] offset:2560
	global_load_dword v99, v2, s[18:19] offset:2816
	global_load_dword v100, v2, s[18:19] offset:3072
	global_load_dword v101, v2, s[18:19] offset:3328
	global_load_dword v102, v2, s[18:19] offset:3584
	global_load_dword v103, v2, s[18:19] offset:3840
	s_add_u32 s18, s18, 0x2000
	s_addc_u32 s19, s19, 0
	v_readlane_b32 s14, v11, 40
	v_readlane_b32 s15, v106, 40
	v_pk_fma_f32 v[108:109], v[132:133], s[10:11], v[108:109] op_sel_hi:[0,1,1]
	v_readlane_b32 s16, v12, 40
	v_readlane_b32 s17, v107, 40
	v_pk_fma_f32 v[108:109], v[132:133], s[12:13], v[108:109] op_sel:[1,0,0] op_sel_hi:[1,1,1]
	v_readlane_b32 s10, v1, 41
	v_readlane_b32 s11, v104, 41
	v_pk_fma_f32 v[108:109], v[134:135], s[14:15], v[108:109] op_sel_hi:[0,1,1]
	v_readlane_b32 s12, v10, 41
	v_readlane_b32 s13, v105, 41
	v_pk_fma_f32 v[108:109], v[134:135], s[16:17], v[108:109] op_sel:[1,0,0] op_sel_hi:[1,1,1]
	v_readlane_b32 s14, v11, 41
	v_readlane_b32 s15, v106, 41
	v_pk_fma_f32 v[108:109], v[136:137], s[10:11], v[108:109] op_sel_hi:[0,1,1]
	v_readlane_b32 s16, v12, 41
	v_readlane_b32 s17, v107, 41
	v_pk_fma_f32 v[108:109], v[136:137], s[12:13], v[108:109] op_sel:[1,0,0] op_sel_hi:[1,1,1]
	v_readlane_b32 s10, v1, 42
	v_readlane_b32 s11, v104, 42
	v_pk_fma_f32 v[108:109], v[138:139], s[14:15], v[108:109] op_sel_hi:[0,1,1]
	v_readlane_b32 s12, v10, 42
	v_readlane_b32 s13, v105, 42
	v_pk_fma_f32 v[108:109], v[138:139], s[16:17], v[108:109] op_sel:[1,0,0] op_sel_hi:[1,1,1]
	v_readlane_b32 s14, v11, 42
	v_readlane_b32 s15, v106, 42
	v_pk_fma_f32 v[108:109], v[140:141], s[10:11], v[108:109] op_sel_hi:[0,1,1]
	v_readlane_b32 s16, v12, 42
	v_readlane_b32 s17, v107, 42
	v_pk_fma_f32 v[108:109], v[140:141], s[12:13], v[108:109] op_sel:[1,0,0] op_sel_hi:[1,1,1]
	v_readlane_b32 s10, v1, 43
	v_readlane_b32 s11, v104, 43
	v_pk_fma_f32 v[108:109], v[142:143], s[14:15], v[108:109] op_sel_hi:[0,1,1]
	v_readlane_b32 s12, v10, 43
	v_readlane_b32 s13, v105, 43
	v_pk_fma_f32 v[108:109], v[142:143], s[16:17], v[108:109] op_sel:[1,0,0] op_sel_hi:[1,1,1]
	v_readlane_b32 s14, v11, 43
	v_readlane_b32 s15, v106, 43
	v_pk_fma_f32 v[108:109], v[144:145], s[10:11], v[108:109] op_sel_hi:[0,1,1]
	v_readlane_b32 s16, v12, 43
	v_readlane_b32 s17, v107, 43
	v_pk_fma_f32 v[108:109], v[144:145], s[12:13], v[108:109] op_sel:[1,0,0] op_sel_hi:[1,1,1]
	v_readlane_b32 s10, v1, 44
	v_readlane_b32 s11, v104, 44
	v_pk_fma_f32 v[108:109], v[146:147], s[14:15], v[108:109] op_sel_hi:[0,1,1]
	v_readlane_b32 s12, v10, 44
	v_readlane_b32 s13, v105, 44
	v_pk_fma_f32 v[108:109], v[146:147], s[16:17], v[108:109] op_sel:[1,0,0] op_sel_hi:[1,1,1]
	s_waitcnt vmcnt(32)
; __global__ void __launch_bounds__(512, 2) mega(Args a) {
;     ...
; #pragma unroll 16
;                     for (int jj = 0; jj < 64; ++jj) {
;                         acc += __int_as_float(__builtin_amdgcn_readlane(__float_as_int(h0), jj)) * w2[(jj * 4 + 0) * 64];
;                         acc += __int_as_float(__builtin_amdgcn_readlane(__float_as_int(h1), jj)) * w2[(jj * 4 + 1) * 64];
;                         acc += __int_as_float(__builtin_amdgcn_readlane(__float_as_int(h2), jj)) * w2[(jj * 4 + 2) * 64];
;                         acc += __int_as_float(__builtin_amdgcn_readlane(__float_as_int(h3), jj)) * w2[(jj * 4 + 3) * 64]; }
	global_load_dword v132, v2, s[18:19] offset:-4096
	global_load_dword v133, v2, s[18:19] offset:-3840
	global_load_dword v134, v2, s[18:19] offset:-3584
	global_load_dword v135, v2, s[18:19] offset:-3328
	global_load_dword v136, v2, s[18:19] offset:-3072
	global_load_dword v137, v2, s[18:19] offset:-2816
	global_load_dword v138, v2, s[18:19] offset:-2560
	global_load_dword v139, v2, s[18:19] offset:-2304
	global_load_dword v140, v2, s[18:19] offset:-2048
	global_load_dword v141, v2, s[18:19] offset:-1792
	global_load_dword v142, v2, s[18:19] offset:-1536
	global_load_dword v143, v2, s[18:19] offset:-1280
	global_load_dword v144, v2, s[18:19] offset:-1024
	global_load_dword v145, v2, s[18:19] offset:-768
	global_load_dword v146, v2, s[18:19] offset:-512
	global_load_dword v147, v2, s[18:19] offset:-256
	v_readlane_b32 s14, v11, 44
	v_readlane_b32 s15, v106, 44
	v_pk_fma_f32 v[108:109], v[148:149], s[10:11], v[108:109] op_sel_hi:[0,1,1]
	v_readlane_b32 s16, v12, 44
	v_readlane_b32 s17, v107, 44
	v_pk_fma_f32 v[108:109], v[148:149], s[12:13], v[108:109] op_sel:[1,0,0] op_sel_hi:[1,1,1]
	v_readlane_b32 s10, v1, 45
	v_readlane_b32 s11, v104, 45
	v_pk_fma_f32 v[108:109], v[150:151], s[14:15], v[108:109] op_sel_hi:[0,1,1]
	v_readlane_b32 s12, v10, 45
	v_readlane_b32 s13, v105, 45
	v_pk_fma_f32 v[108:109], v[150:151], s[16:17], v[108:109] op_sel:[1,0,0] op_sel_hi:[1,1,1]
	v_readlane_b32 s14, v11, 45
	v_readlane_b32 s15, v106, 45
	v_pk_fma_f32 v[108:109], v[152:153], s[10:11], v[108:109] op_sel_hi:[0,1,1]
	v_readlane_b32 s16, v12, 45
	v_readlane_b32 s17, v107, 45
	v_pk_fma_f32 v[108:109], v[152:153], s[12:13], v[108:109] op_sel:[1,0,0] op_sel_hi:[1,1,1]
	v_readlane_b32 s10, v1, 46
	v_readlane_b32 s11, v104, 46
	v_pk_fma_f32 v[108:109], v[154:155], s[14:15], v[108:109] op_sel_hi:[0,1,1]
	v_readlane_b32 s12, v10, 46
	v_readlane_b32 s13, v105, 46
	v_pk_fma_f32 v[108:109], v[154:155], s[16:17], v[108:109] op_sel:[1,0,0] op_sel_hi:[1,1,1]
	v_readlane_b32 s14, v11, 46
	v_readlane_b32 s15, v106, 46
	v_pk_fma_f32 v[108:109], v[156:157], s[10:11], v[108:109] op_sel_hi:[0,1,1]
	v_readlane_b32 s16, v12, 46
	v_readlane_b32 s17, v107, 46
	v_pk_fma_f32 v[108:109], v[156:157], s[12:13], v[108:109] op_sel:[1,0,0] op_sel_hi:[1,1,1]
	v_readlane_b32 s10, v1, 47
	v_readlane_b32 s11, v104, 47
	v_pk_fma_f32 v[108:109], v[158:159], s[14:15], v[108:109] op_sel_hi:[0,1,1]
	v_readlane_b32 s12, v10, 47
	v_readlane_b32 s13, v105, 47
	v_pk_fma_f32 v[108:109], v[158:159], s[16:17], v[108:109] op_sel:[1,0,0] op_sel_hi:[1,1,1]
	v_readlane_b32 s14, v11, 47
	v_readlane_b32 s15, v106, 47
	v_pk_fma_f32 v[108:109], v[160:161], s[10:11], v[108:109] op_sel_hi:[0,1,1]
	v_readlane_b32 s16, v12, 47
	v_readlane_b32 s17, v107, 47
	v_pk_fma_f32 v[108:109], v[160:161], s[12:13], v[108:109] op_sel:[1,0,0] op_sel_hi:[1,1,1]
	v_readlane_b32 s10, v1, 48
	v_readlane_b32 s11, v104, 48
	v_pk_fma_f32 v[108:109], v[162:163], s[14:15], v[108:109] op_sel_hi:[0,1,1]
	v_readlane_b32 s12, v10, 48
	v_readlane_b32 s13, v105, 48
	v_pk_fma_f32 v[108:109], v[162:163], s[16:17], v[108:109] op_sel:[1,0,0] op_sel_hi:[1,1,1]
	s_waitcnt vmcnt(32)
	global_load_dword v148, v2, s[18:19]
	global_load_dword v149, v2, s[18:19] offset:256
	global_load_dword v150, v2, s[18:19] offset:512
	global_load_dword v151, v2, s[18:19] offset:768
	global_load_dword v152, v2, s[18:19] offset:1024
	global_load_dword v153, v2, s[18:19] offset:1280
	global_load_dword v154, v2, s[18:19] offset:1536
	global_load_dword v155, v2, s[18:19] offset:1792
	global_load_dword v156, v2, s[18:19] offset:2048
	global_load_dword v157, v2, s[18:19] offset:2304
	global_load_dword v158, v2, s[18:19] offset:2560
	global_load_dword v159, v2, s[18:19] offset:2816
	global_load_dword v160, v2, s[18:19] offset:3072
	global_load_dword v161, v2, s[18:19] offset:3328
	global_load_dword v162, v2, s[18:19] offset:3584
	global_load_dword v163, v2, s[18:19] offset:3840
	s_add_u32 s18, s18, 0x2000
	s_addc_u32 s19, s19, 0
	v_readlane_b32 s14, v11, 48
	v_readlane_b32 s15, v106, 48
	v_pk_fma_f32 v[108:109], v[72:73], s[10:11], v[108:109] op_sel_hi:[0,1,1]
	v_readlane_b32 s16, v12, 48
	v_readlane_b32 s17, v107, 48
	v_pk_fma_f32 v[108:109], v[72:73], s[12:13], v[108:109] op_sel:[1,0,0] op_sel_hi:[1,1,1]
	v_readlane_b32 s10, v1, 49
	v_readlane_b32 s11, v104, 49
	v_pk_fma_f32 v[108:109], v[74:75], s[14:15], v[108:109] op_sel_hi:[0,1,1]
	v_readlane_b32 s12, v10, 49
	v_readlane_b32 s13, v105, 49
	v_pk_fma_f32 v[108:109], v[74:75], s[16:17], v[108:109] op_sel:[1,0,0] op_sel_hi:[1,1,1]
	v_readlane_b32 s14, v11, 49
	v_readlane_b32 s15, v106, 49
	v_pk_fma_f32 v[108:109], v[76:77], s[10:11], v[108:109] op_sel_hi:[0,1,1]
	v_readlane_b32 s16, v12, 49
	v_readlane_b32 s17, v107, 49
	v_pk_fma_f32 v[108:109], v[76:77], s[12:13], v[108:109] op_sel:[1,0,0] op_sel_hi:[1,1,1]
	v_readlane_b32 s10, v1, 50
	v_readlane_b32 s11, v104, 50
	v_pk_fma_f32 v[108:109], v[78:79], s[14:15], v[108:109] op_sel_hi:[0,1,1]
	v_readlane_b32 s12, v10, 50
	v_readlane_b32 s13, v105, 50
	v_pk_fma_f32 v[108:109], v[78:79], s[16:17], v[108:109] op_sel:[1,0,0] op_sel_hi:[1,1,1]
	v_readlane_b32 s14, v11, 50
	v_readlane_b32 s15, v106, 50
	v_pk_fma_f32 v[108:109], v[80:81], s[10:11], v[108:109] op_sel_hi:[0,1,1]
	v_readlane_b32 s16, v12, 50
	v_readlane_b32 s17, v107, 50
	v_pk_fma_f32 v[108:109], v[80:81], s[12:13], v[108:109] op_sel:[1,0,0] op_sel_hi:[1,1,1]
	v_readlane_b32 s10, v1, 51
	v_readlane_b32 s11, v104, 51
	v_pk_fma_f32 v[108:109], v[82:83], s[14:15], v[108:109] op_sel_hi:[0,1,1]
	v_readlane_b32 s12, v10, 51
	v_readlane_b32 s13, v105, 51
	v_pk_fma_f32 v[108:109], v[82:83], s[16:17], v[108:109] op_sel:[1,0,0] op_sel_hi:[1,1,1]
	v_readlane_b32 s14, v11, 51
	v_readlane_b32 s15, v106, 51
	v_pk_fma_f32 v[108:109], v[84:85], s[10:11], v[108:109] op_sel_hi:[0,1,1]
	v_readlane_b32 s16, v12, 51
	v_readlane_b32 s17, v107, 51
	v_pk_fma_f32 v[108:109], v[84:85], s[12:13], v[108:109] op_sel:[1,0,0] op_sel_hi:[1,1,1]
	v_readlane_b32 s10, v1, 52
	v_readlane_b32 s11, v104, 52
	v_pk_fma_f32 v[108:109], v[86:87], s[14:15], v[108:109] op_sel_hi:[0,1,1]
	v_readlane_b32 s12, v10, 52
	v_readlane_b32 s13, v105, 52
	v_pk_fma_f32 v[108:109], v[86:87], s[16:17], v[108:109] op_sel:[1,0,0] op_sel_hi:[1,1,1]
	s_waitcnt vmcnt(32)
; __device__ __forceinline__ unsigned cvt_pk_bf16(float lo, float hi) { unsigned r; asm volatile("v_cvt_pk_bf16_f32 %0, %1, %2" : "=v"(r) : "v"(lo), "v"(hi)); return r; }
; __device__ __forceinline__ float wave_sum(float x) { return x32sum(x16sum(sum16(x))); }
; #define INP(i) ((const float*)ldp(tab, (i)))
; __global__ void __launch_bounds__(512, 2) mega(Args a) {
;     ...
; #pragma unroll 16
;                     for (int jj = 0; jj < 64; ++jj) {
;                         acc += __int_as_float(__builtin_amdgcn_readlane(__float_as_int(h0), jj)) * w2[(jj * 4 + 0) * 64];
;                         acc += __int_as_float(__builtin_amdgcn_readlane(__float_as_int(h1), jj)) * w2[(jj * 4 + 1) * 64];
;                         acc += __int_as_float(__builtin_amdgcn_readlane(__float_as_int(h2), jj)) * w2[(jj * 4 + 2) * 64];
;                         acc += __int_as_float(__builtin_amdgcn_readlane(__float_as_int(h3), jj)) * w2[(jj * 4 + 3) * 64]; }
;                 }
;                 if (kv == 0) { const float rr = __builtin_amdgcn_rsqf(wave_sum(acc * acc) * (1.0f / 64.0f) + EPS); const float y = acc * rr * INP(I_GKC)[lane];
;                     KC[((size_t)gg * 512 + i) * 64 + lane] = (bf16_t)(cvt_pk_bf16(y, 0.f) & 0xffffu); }
;                 else VCT[((size_t)gg * 64 + lane) * 512 + i] = (bf16_t)(cvt_pk_bf16(acc, 0.f) & 0xffffu);
	v_readlane_b32 s14, v11, 52
	v_readlane_b32 s15, v106, 52
	v_pk_fma_f32 v[108:109], v[88:89], s[10:11], v[108:109] op_sel_hi:[0,1,1]
	v_readlane_b32 s16, v12, 52
	v_readlane_b32 s17, v107, 52
	v_pk_fma_f32 v[108:109], v[88:89], s[12:13], v[108:109] op_sel:[1,0,0] op_sel_hi:[1,1,1]
	v_readlane_b32 s10, v1, 53
	v_readlane_b32 s11, v104, 53
	v_pk_fma_f32 v[108:109], v[90:91], s[14:15], v[108:109] op_sel_hi:[0,1,1]
	v_readlane_b32 s12, v10, 53
	v_readlane_b32 s13, v105, 53
	v_pk_fma_f32 v[108:109], v[90:91], s[16:17], v[108:109] op_sel:[1,0,0] op_sel_hi:[1,1,1]
	v_readlane_b32 s14, v11, 53
	v_readlane_b32 s15, v106, 53
	v_pk_fma_f32 v[108:109], v[92:93], s[10:11], v[108:109] op_sel_hi:[0,1,1]
	v_readlane_b32 s16, v12, 53
	v_readlane_b32 s17, v107, 53
	v_pk_fma_f32 v[108:109], v[92:93], s[12:13], v[108:109] op_sel:[1,0,0] op_sel_hi:[1,1,1]
	v_readlane_b32 s10, v1, 54
	v_readlane_b32 s11, v104, 54
	v_pk_fma_f32 v[108:109], v[94:95], s[14:15], v[108:109] op_sel_hi:[0,1,1]
	v_readlane_b32 s12, v10, 54
	v_readlane_b32 s13, v105, 54
	v_pk_fma_f32 v[108:109], v[94:95], s[16:17], v[108:109] op_sel:[1,0,0] op_sel_hi:[1,1,1]
	v_readlane_b32 s14, v11, 54
	v_readlane_b32 s15, v106, 54
	v_pk_fma_f32 v[108:109], v[96:97], s[10:11], v[108:109] op_sel_hi:[0,1,1]
	v_readlane_b32 s16, v12, 54
	v_readlane_b32 s17, v107, 54
	v_pk_fma_f32 v[108:109], v[96:97], s[12:13], v[108:109] op_sel:[1,0,0] op_sel_hi:[1,1,1]
	v_readlane_b32 s10, v1, 55
	v_readlane_b32 s11, v104, 55
	v_pk_fma_f32 v[108:109], v[98:99], s[14:15], v[108:109] op_sel_hi:[0,1,1]
	v_readlane_b32 s12, v10, 55
	v_readlane_b32 s13, v105, 55
	v_pk_fma_f32 v[108:109], v[98:99], s[16:17], v[108:109] op_sel:[1,0,0] op_sel_hi:[1,1,1]
	v_readlane_b32 s14, v11, 55
	v_readlane_b32 s15, v106, 55
	v_pk_fma_f32 v[108:109], v[100:101], s[10:11], v[108:109] op_sel_hi:[0,1,1]
	v_readlane_b32 s16, v12, 55
	v_readlane_b32 s17, v107, 55
	v_pk_fma_f32 v[108:109], v[100:101], s[12:13], v[108:109] op_sel:[1,0,0] op_sel_hi:[1,1,1]
	v_readlane_b32 s10, v1, 56
	v_readlane_b32 s11, v104, 56
	v_pk_fma_f32 v[108:109], v[102:103], s[14:15], v[108:109] op_sel_hi:[0,1,1]
	v_readlane_b32 s12, v10, 56
	v_readlane_b32 s13, v105, 56
	v_pk_fma_f32 v[108:109], v[102:103], s[16:17], v[108:109] op_sel:[1,0,0] op_sel_hi:[1,1,1]
	s_waitcnt vmcnt(16)
	v_readlane_b32 s14, v11, 56
	v_readlane_b32 s15, v106, 56
	v_pk_fma_f32 v[108:109], v[132:133], s[10:11], v[108:109] op_sel_hi:[0,1,1]
	v_readlane_b32 s16, v12, 56
	v_readlane_b32 s17, v107, 56
	v_pk_fma_f32 v[108:109], v[132:133], s[12:13], v[108:109] op_sel:[1,0,0] op_sel_hi:[1,1,1]
	v_readlane_b32 s10, v1, 57
	v_readlane_b32 s11, v104, 57
	v_pk_fma_f32 v[108:109], v[134:135], s[14:15], v[108:109] op_sel_hi:[0,1,1]
	v_readlane_b32 s12, v10, 57
	v_readlane_b32 s13, v105, 57
	v_pk_fma_f32 v[108:109], v[134:135], s[16:17], v[108:109] op_sel:[1,0,0] op_sel_hi:[1,1,1]
	v_readlane_b32 s14, v11, 57
	v_readlane_b32 s15, v106, 57
	v_pk_fma_f32 v[108:109], v[136:137], s[10:11], v[108:109] op_sel_hi:[0,1,1]
	v_readlane_b32 s16, v12, 57
	v_readlane_b32 s17, v107, 57
	v_pk_fma_f32 v[108:109], v[136:137], s[12:13], v[108:109] op_sel:[1,0,0] op_sel_hi:[1,1,1]
	v_readlane_b32 s10, v1, 58
	v_readlane_b32 s11, v104, 58
	v_pk_fma_f32 v[108:109], v[138:139], s[14:15], v[108:109] op_sel_hi:[0,1,1]
	v_readlane_b32 s12, v10, 58
	v_readlane_b32 s13, v105, 58
	v_pk_fma_f32 v[108:109], v[138:139], s[16:17], v[108:109] op_sel:[1,0,0] op_sel_hi:[1,1,1]
	v_readlane_b32 s14, v11, 58
	v_readlane_b32 s15, v106, 58
	v_pk_fma_f32 v[108:109], v[140:141], s[10:11], v[108:109] op_sel_hi:[0,1,1]
	v_readlane_b32 s16, v12, 58
	v_readlane_b32 s17, v107, 58
	v_pk_fma_f32 v[108:109], v[140:141], s[12:13], v[108:109] op_sel:[1,0,0] op_sel_hi:[1,1,1]
	v_readlane_b32 s10, v1, 59
	v_readlane_b32 s11, v104, 59
	v_pk_fma_f32 v[108:109], v[142:143], s[14:15], v[108:109] op_sel_hi:[0,1,1]
	v_readlane_b32 s12, v10, 59
	v_readlane_b32 s13, v105, 59
	v_pk_fma_f32 v[108:109], v[142:143], s[16:17], v[108:109] op_sel:[1,0,0] op_sel_hi:[1,1,1]
	v_readlane_b32 s14, v11, 59
	v_readlane_b32 s15, v106, 59
	v_pk_fma_f32 v[108:109], v[144:145], s[10:11], v[108:109] op_sel_hi:[0,1,1]
	v_readlane_b32 s16, v12, 59
	v_readlane_b32 s17, v107, 59
	v_pk_fma_f32 v[108:109], v[144:145], s[12:13], v[108:109] op_sel:[1,0,0] op_sel_hi:[1,1,1]
	v_readlane_b32 s10, v1, 60
	v_readlane_b32 s11, v104, 60
	v_pk_fma_f32 v[108:109], v[146:147], s[14:15], v[108:109] op_sel_hi:[0,1,1]
	v_readlane_b32 s12, v10, 60
	v_readlane_b32 s13, v105, 60
	v_pk_fma_f32 v[108:109], v[146:147], s[16:17], v[108:109] op_sel:[1,0,0] op_sel_hi:[1,1,1]
	s_waitcnt vmcnt(0)
	v_readlane_b32 s14, v11, 60
	v_readlane_b32 s15, v106, 60
	v_pk_fma_f32 v[108:109], v[148:149], s[10:11], v[108:109] op_sel_hi:[0,1,1]
	v_readlane_b32 s16, v12, 60
	v_readlane_b32 s17, v107, 60
	v_pk_fma_f32 v[108:109], v[148:149], s[12:13], v[108:109] op_sel:[1,0,0] op_sel_hi:[1,1,1]
	v_readlane_b32 s10, v1, 61
	v_readlane_b32 s11, v104, 61
	v_pk_fma_f32 v[108:109], v[150:151], s[14:15], v[108:109] op_sel_hi:[0,1,1]
	v_readlane_b32 s12, v10, 61
	v_readlane_b32 s13, v105, 61
	v_pk_fma_f32 v[108:109], v[150:151], s[16:17], v[108:109] op_sel:[1,0,0] op_sel_hi:[1,1,1]
	v_readlane_b32 s14, v11, 61
	v_readlane_b32 s15, v106, 61
	v_pk_fma_f32 v[108:109], v[152:153], s[10:11], v[108:109] op_sel_hi:[0,1,1]
	v_readlane_b32 s16, v12, 61
	v_readlane_b32 s17, v107, 61
	v_pk_fma_f32 v[108:109], v[152:153], s[12:13], v[108:109] op_sel:[1,0,0] op_sel_hi:[1,1,1]
	v_readlane_b32 s10, v1, 62
	v_readlane_b32 s11, v104, 62
	v_pk_fma_f32 v[108:109], v[154:155], s[14:15], v[108:109] op_sel_hi:[0,1,1]
	v_readlane_b32 s12, v10, 62
	v_readlane_b32 s13, v105, 62
	v_pk_fma_f32 v[108:109], v[154:155], s[16:17], v[108:109] op_sel:[1,0,0] op_sel_hi:[1,1,1]
	v_readlane_b32 s14, v11, 62
	v_readlane_b32 s15, v106, 62
	v_pk_fma_f32 v[108:109], v[156:157], s[10:11], v[108:109] op_sel_hi:[0,1,1]
	v_readlane_b32 s16, v12, 62
	v_readlane_b32 s17, v107, 62
	v_pk_fma_f32 v[108:109], v[156:157], s[12:13], v[108:109] op_sel:[1,0,0] op_sel_hi:[1,1,1]
	v_readlane_b32 s10, v1, 63
	v_readlane_b32 s11, v104, 63
	v_pk_fma_f32 v[108:109], v[158:159], s[14:15], v[108:109] op_sel_hi:[0,1,1]
	v_readlane_b32 s12, v10, 63
	v_readlane_b32 s13, v105, 63
	v_pk_fma_f32 v[108:109], v[158:159], s[16:17], v[108:109] op_sel:[1,0,0] op_sel_hi:[1,1,1]
	v_readlane_b32 s14, v11, 63
	v_readlane_b32 s15, v106, 63
	v_pk_fma_f32 v[108:109], v[160:161], s[10:11], v[108:109] op_sel_hi:[0,1,1]
	v_readlane_b32 s16, v12, 63
	v_readlane_b32 s17, v107, 63
	v_pk_fma_f32 v[108:109], v[160:161], s[12:13], v[108:109] op_sel:[1,0,0] op_sel_hi:[1,1,1]
	v_pk_fma_f32 v[108:109], v[162:163], s[14:15], v[108:109] op_sel_hi:[0,1,1]
	v_pk_fma_f32 v[108:109], v[162:163], s[16:17], v[108:109] op_sel:[1,0,0] op_sel_hi:[1,1,1]
	v_mov_b32_e32 v13, v108
	v_mov_b32_e32 v165, v109

; __global__ void __launch_bounds__(512, 2) mega(Args a) {
;     ...
;     for (int ph = a.ph_lo; ; ++ph) {
;         asm volatile("" ::: "memory");
;         const int ph_hi = __builtin_amdgcn_readfirstlane((int)(tab[31] >> 32));
;         if (ph >= ph_hi) break;
.Ltramp_1094:
	s_branch .LBB0_1094
